# MFMA A/B operands placed in different VGPR banks (register renumbering only)
# baseline (speedup 1.0000x reference)
.Lmy_ck_nz:
	s_mov_b32 s100, 0xe000
	s_cmp_eq_u32 s23, 0
	s_cselect_b32 s100, 0x1c000, s100
	s_mov_b32 s101, 0x12e00
	s_cselect_b32 s101, 0x22100, s101
	s_lshl_b32 s96, s23, 13
	s_add_i32 s97, s96, 0x18000
	s_add_i32 s96, s96, 0xa000
	v_add_u32_e32 v225, s100, v1
	v_add_u32_e32 v236, s100, v0
	v_add_u32_e32 v226, s100, v2
	v_add_u32_e32 v227, s100, v3
	v_add_u32_e32 v228, s100, v4
	v_add_u32_e32 v229, s100, v5
	v_add_u32_e32 v237, s100, v6
	v_add_u32_e32 v238, s100, v7
	v_add_u32_e32 v230, s96, v8
	v_add_u32_e32 v239, s96, v9
	v_add_u32_e32 v231, s97, v8
	v_add_u32_e32 v26, s101, v1
	v_add_u32_e32 v27, s101, v0
	v_add_u32_e32 v28, s101, v2
	v_add_u32_e32 v29, s101, v3
	v_add_u32_e32 v30, s101, v4
	v_add_u32_e32 v31, s101, v5
	v_add_u32_e32 v32, s101, v6
	v_add_u32_e32 v33, s101, v7
	ds_read_b64 v[80:81], v237
	ds_read_b64 v[82:83], v238
	ds_read_b32 v84, v230
	ds_read_b32 v85, v230 offset:256
	ds_read_b32 v86, v230 offset:512
	ds_read_b32 v87, v230 offset:768
	ds_read_b32 v38, v239
	ds_read_b32 v39, v239 offset:256
	ds_read_b128 v[90:93], v225
	ds_read_b128 v[94:97], v225 offset:1024
	ds_read_b128 v[98:101], v225 offset:2048
	ds_read_b128 v[102:105], v225 offset:3072
	ds_read_b32 v106, v227 offset:4
	ds_read_b32 v107, v227 offset:76
	ds_read_b64 v[108:109], v227 offset:8
	ds_read_b64 v[110:111], v227 offset:40
	ds_read_b32 v128, v229 offset:4
	ds_read_b32 v129, v229 offset:76
	ds_read_b64 v[130:131], v229 offset:8
	ds_read_b64 v[132:133], v229 offset:40
	ds_read_b64 v[112:113], v228
	ds_read_b64 v[114:115], v228 offset:32
	ds_read_b64 v[116:117], v228 offset:64
	ds_read_b64 v[118:119], v228 offset:96
	ds_read_b64 v[120:121], v228 offset:8
	ds_read_b64 v[122:123], v228 offset:40
	ds_read_b64 v[124:125], v228 offset:72
	ds_read_b64 v[126:127], v228 offset:104
	s_waitcnt lgkmcnt(15)
	v_mfma_f32_16x16x4_f32 v[240:243], v80, v38, 0
	v_mfma_f32_16x16x4_f32 v[240:243], v81, v39, v[240:243]
	v_mfma_f32_16x16x4_f32 v[240:243], v90, v208, v[240:243]
	ds_read_b128 v[190:193], v236 offset:4096
	ds_read_b128 v[194:197], v236 offset:5120
	v_mfma_f32_16x16x4_f32 v[244:247], v91, v209, 0
	ds_read_b128 v[198:201], v236 offset:6144
	ds_read_b128 v[202:205], v236 offset:7168
	v_mfma_f32_16x16x4_f32 v[240:243], v92, v210, v[240:243]
	ds_read_b64 v[134:135], v237 offset:9984
	ds_read_b64 v[136:137], v238 offset:9984
	v_mfma_f32_16x16x4_f32 v[244:247], v93, v211, v[244:247]
	ds_read_b32 v138, v230 offset:2048
	ds_read_b32 v139, v230 offset:2304
	v_mfma_f32_16x16x4_f32 v[240:243], v94, v212, v[240:243]
	ds_read_b32 v140, v230 offset:2560
	ds_read_b32 v141, v230 offset:2816
	v_mfma_f32_16x16x4_f32 v[244:247], v95, v213, v[244:247]
	ds_read_b32 v46, v239 offset:2048
	ds_read_b32 v47, v239 offset:2304
	v_mfma_f32_16x16x4_f32 v[240:243], v96, v214, v[240:243]
	ds_read_b128 v[144:147], v225 offset:9984
	ds_read_b128 v[148:151], v225 offset:11008
	v_mfma_f32_16x16x4_f32 v[244:247], v97, v215, v[244:247]
	ds_read_b128 v[152:155], v225 offset:12032
	ds_read_b128 v[156:159], v225 offset:13056
	v_mfma_f32_16x16x4_f32 v[240:243], v98, v216, v[240:243]
	ds_read_b32 v160, v227 offset:9988
	ds_read_b32 v161, v227 offset:10060
	v_mfma_f32_16x16x4_f32 v[244:247], v99, v217, v[244:247]
	ds_read_b64 v[162:163], v227 offset:9992
	ds_read_b64 v[164:165], v227 offset:10024
	v_mfma_f32_16x16x4_f32 v[240:243], v100, v218, v[240:243]
	ds_read_b32 v182, v229 offset:9988
	ds_read_b32 v183, v229 offset:10060
	v_mfma_f32_16x16x4_f32 v[244:247], v101, v219, v[244:247]
	ds_read_b64 v[184:185], v229 offset:9992
	ds_read_b64 v[186:187], v229 offset:10024
	v_mfma_f32_16x16x4_f32 v[240:243], v102, v220, v[240:243]
	ds_read_b64 v[166:167], v228 offset:9984
	ds_read_b64 v[168:169], v228 offset:10016
	v_mfma_f32_16x16x4_f32 v[244:247], v103, v221, v[244:247]
	ds_read_b64 v[170:171], v228 offset:10048
	ds_read_b64 v[172:173], v228 offset:10080
	v_mfma_f32_16x16x4_f32 v[240:243], v104, v222, v[240:243]
	ds_read_b64 v[174:175], v228 offset:9992
	ds_read_b64 v[176:177], v228 offset:10024
	v_mfma_f32_16x16x4_f32 v[244:247], v105, v223, v[244:247]
	ds_read_b64 v[178:179], v228 offset:10056
	ds_read_b64 v[180:181], v228 offset:10088
	s_nop 7
	v_pk_add_f32 v[240:241], v[240:241], v[244:245]
	v_pk_add_f32 v[242:243], v[242:243], v[246:247]
	v_fmac_f32_e32 v241, v106, v240
	s_waitcnt lgkmcnt(13)
	v_pk_fma_f32 v[242:243], v[108:109], v[240:241], v[242:243] op_sel:[0,0,0] op_sel_hi:[1,0,1]
	v_pk_fma_f32 v[242:243], v[110:111], v[240:241], v[242:243] op_sel:[0,1,0] op_sel_hi:[1,1,1]
	v_fmac_f32_e32 v243, v107, v242
	ds_bpermute_b32 v40, v232, v240
	ds_bpermute_b32 v41, v232, v241
	ds_bpermute_b32 v42, v232, v242
	ds_bpermute_b32 v43, v232, v243
	ds_read_b128 v[90:93], v226
	ds_read_b128 v[94:97], v226 offset:64
	ds_read_b128 v[98:101], v226 offset:128
	ds_read_b128 v[102:105], v226 offset:192
	v_mfma_f32_16x16x4_f32 v[72:75], v134, v46, 0
	v_mfma_f32_16x16x4_f32 v[72:75], v135, v47, v[72:75]
	s_waitcnt lgkmcnt(6)
	v_pk_fma_f32 v[240:241], v[112:113], v[40:41], v[240:241] op_sel:[0,0,0] op_sel_hi:[1,0,1]
	v_pk_fma_f32 v[240:241], v[114:115], v[40:41], v[240:241] op_sel:[0,1,0] op_sel_hi:[1,1,1]
	s_waitcnt lgkmcnt(4)
	v_pk_fma_f32 v[240:241], v[116:117], v[42:43], v[240:241] op_sel:[0,0,0] op_sel_hi:[1,0,1]
	v_pk_fma_f32 v[240:241], v[118:119], v[42:43], v[240:241] op_sel:[0,1,0] op_sel_hi:[1,1,1]
	v_pk_fma_f32 v[242:243], v[120:121], v[40:41], v[242:243] op_sel:[0,0,0] op_sel_hi:[1,0,1]
	v_pk_fma_f32 v[242:243], v[122:123], v[40:41], v[242:243] op_sel:[0,1,0] op_sel_hi:[1,1,1]
	v_pk_fma_f32 v[242:243], v[124:125], v[42:43], v[242:243] op_sel:[0,0,0] op_sel_hi:[1,0,1]
	v_pk_fma_f32 v[242:243], v[126:127], v[42:43], v[242:243] op_sel:[0,1,0] op_sel_hi:[1,1,1]
	v_fmac_f32_e32 v241, v128, v240
	v_pk_fma_f32 v[242:243], v[130:131], v[240:241], v[242:243] op_sel:[0,0,0] op_sel_hi:[1,0,1]
	v_pk_fma_f32 v[242:243], v[132:133], v[240:241], v[242:243] op_sel:[0,1,0] op_sel_hi:[1,1,1]
	v_fmac_f32_e32 v243, v129, v242
	v_cndmask_b32_e64 v56, v240, v84, s[98:99]
	v_cndmask_b32_e64 v57, v241, v85, s[98:99]
	v_cndmask_b32_e64 v58, v242, v86, s[98:99]
	v_cndmask_b32_e64 v59, v243, v87, s[98:99]
	v_mov_b32_e32 v252, v240
	v_mov_b32_e32 v253, v241
	v_mov_b32_e32 v254, v242
	v_mov_b32_e32 v255, v243
	v_mfma_f32_16x16x4_f32 v[208:211], v190, v56, v[208:211]
	v_mfma_f32_16x16x4_f32 v[212:215], v194, v56, v[212:215]
	v_mfma_f32_16x16x4_f32 v[216:219], v198, v56, v[216:219]
	v_mfma_f32_16x16x4_f32 v[220:223], v202, v56, v[220:223]
	v_permlane32_swap_b32_e32 v252, v254
	v_permlane32_swap_b32_e32 v253, v255
	v_mfma_f32_16x16x4_f32 v[208:211], v191, v57, v[208:211]
	v_mfma_f32_16x16x4_f32 v[212:215], v195, v57, v[212:215]
	v_mfma_f32_16x16x4_f32 v[216:219], v199, v57, v[216:219]
	v_mfma_f32_16x16x4_f32 v[220:223], v203, v57, v[220:223]
	v_mfma_f32_16x16x4_f32 v[208:211], v192, v58, v[208:211]
	v_mfma_f32_16x16x4_f32 v[212:215], v196, v58, v[212:215]
	v_mfma_f32_16x16x4_f32 v[216:219], v200, v58, v[216:219]
	v_mfma_f32_16x16x4_f32 v[220:223], v204, v58, v[220:223]
	v_mfma_f32_16x16x4_f32 v[208:211], v193, v59, v[208:211]
	v_mfma_f32_16x16x4_f32 v[212:215], v197, v59, v[212:215]
	v_mfma_f32_16x16x4_f32 v[216:219], v201, v59, v[216:219]
	v_mfma_f32_16x16x4_f32 v[220:223], v205, v59, v[220:223]
	v_mfma_f32_16x16x4_f32 v[248:251], v82, v252, v[240:243]
	v_mfma_f32_16x16x4_f32 v[248:251], v83, v253, v[248:251]
	s_waitcnt lgkmcnt(0)
	s_nop 4
	v_pk_mul_f32 v[208:209], v[208:209], v[90:91]
	v_pk_mul_f32 v[210:211], v[210:211], v[92:93]
	s_nop 0
	v_mfma_f32_16x16x4_f32 v[72:75], v144, v208, v[72:75]
	v_pk_mul_f32 v[212:213], v[212:213], v[94:95]
	v_mfma_f32_16x16x4_f32 v[244:247], v145, v209, 0
	v_pk_mul_f32 v[214:215], v[214:215], v[96:97]
	v_mfma_f32_16x16x4_f32 v[72:75], v146, v210, v[72:75]
	v_pk_mul_f32 v[216:217], v[216:217], v[98:99]
	v_mfma_f32_16x16x4_f32 v[244:247], v147, v211, v[244:247]
	v_pk_mul_f32 v[218:219], v[218:219], v[100:101]
	v_mfma_f32_16x16x4_f32 v[72:75], v148, v212, v[72:75]
	v_pk_mul_f32 v[220:221], v[220:221], v[102:103]
	v_mfma_f32_16x16x4_f32 v[244:247], v149, v213, v[244:247]
	v_pk_mul_f32 v[222:223], v[222:223], v[104:105]
	v_mfma_f32_16x16x4_f32 v[72:75], v150, v214, v[72:75]
	s_mov_b64 exec, s[98:99]
	ds_write_b32 v231, v248
	ds_write_b32 v231, v249 offset:256
	ds_write_b32 v231, v250 offset:512
	ds_write_b32 v231, v251 offset:768
	s_mov_b64 exec, -1
	ds_read_b128 v[190:193], v236 offset:14080
	ds_read_b128 v[194:197], v236 offset:15104
	v_mfma_f32_16x16x4_f32 v[244:247], v151, v215, v[244:247]
	ds_read_b128 v[198:201], v236 offset:16128
	ds_read_b128 v[202:205], v236 offset:17152
	v_mfma_f32_16x16x4_f32 v[72:75], v152, v216, v[72:75]
	ds_read_b64 v[80:81], v32
	ds_read_b64 v[82:83], v33
	ds_read_b32 v84, v230 offset:4096
	ds_read_b32 v85, v230 offset:4352
	v_mfma_f32_16x16x4_f32 v[244:247], v153, v217, v[244:247]
	ds_read_b32 v86, v230 offset:4608
	ds_read_b32 v87, v230 offset:4864
	ds_read_b32 v38, v239 offset:4096
	ds_read_b32 v39, v239 offset:4352
	v_mfma_f32_16x16x4_f32 v[72:75], v154, v218, v[72:75]
	ds_read_b128 v[90:93], v26
	ds_read_b128 v[94:97], v26 offset:1024
	ds_read_b128 v[98:101], v26 offset:2048
	ds_read_b128 v[102:105], v26 offset:3072
	v_mfma_f32_16x16x4_f32 v[244:247], v155, v219, v[244:247]
	ds_read_b32 v106, v29 offset:4
	ds_read_b32 v107, v29 offset:76
	ds_read_b64 v[108:109], v29 offset:8
	ds_read_b64 v[110:111], v29 offset:40
	v_mfma_f32_16x16x4_f32 v[72:75], v156, v220, v[72:75]
	ds_read_b32 v128, v31 offset:4
	ds_read_b32 v129, v31 offset:76
	ds_read_b64 v[130:131], v31 offset:8
	ds_read_b64 v[132:133], v31 offset:40
	v_mfma_f32_16x16x4_f32 v[244:247], v157, v221, v[244:247]
	ds_read_b64 v[112:113], v30
	ds_read_b64 v[114:115], v30 offset:32
	ds_read_b64 v[116:117], v30 offset:64
	ds_read_b64 v[118:119], v30 offset:96
	v_mfma_f32_16x16x4_f32 v[72:75], v158, v222, v[72:75]
	ds_read_b64 v[120:121], v30 offset:8
	ds_read_b64 v[122:123], v30 offset:40
	ds_read_b64 v[124:125], v30 offset:72
	ds_read_b64 v[126:127], v30 offset:104
	v_mfma_f32_16x16x4_f32 v[244:247], v159, v223, v[244:247]
	s_nop 9
	v_pk_add_f32 v[72:73], v[72:73], v[244:245]
	v_pk_add_f32 v[74:75], v[74:75], v[246:247]
	v_fmac_f32_e32 v73, v160, v72
	v_pk_fma_f32 v[74:75], v[162:163], v[72:73], v[74:75] op_sel:[0,0,0] op_sel_hi:[1,0,1]
	v_pk_fma_f32 v[74:75], v[164:165], v[72:73], v[74:75] op_sel:[0,1,0] op_sel_hi:[1,1,1]
	v_fmac_f32_e32 v75, v161, v74
	ds_bpermute_b32 v40, v232, v72
	ds_bpermute_b32 v41, v232, v73
	ds_bpermute_b32 v42, v232, v74
	ds_bpermute_b32 v43, v232, v75
	ds_read_b128 v[144:147], v226 offset:9984
	ds_read_b128 v[148:151], v226 offset:10048
	ds_read_b128 v[152:155], v226 offset:10112
	ds_read_b128 v[156:159], v226 offset:10176
	s_waitcnt lgkmcnt(14)
	v_mfma_f32_16x16x4_f32 v[240:243], v80, v38, 0
	v_mfma_f32_16x16x4_f32 v[240:243], v81, v39, v[240:243]
	s_waitcnt lgkmcnt(6)
	v_pk_fma_f32 v[72:73], v[166:167], v[40:41], v[72:73] op_sel:[0,0,0] op_sel_hi:[1,0,1]
	v_pk_fma_f32 v[72:73], v[168:169], v[40:41], v[72:73] op_sel:[0,1,0] op_sel_hi:[1,1,1]
	s_waitcnt lgkmcnt(4)
	v_pk_fma_f32 v[72:73], v[170:171], v[42:43], v[72:73] op_sel:[0,0,0] op_sel_hi:[1,0,1]
	v_pk_fma_f32 v[72:73], v[172:173], v[42:43], v[72:73] op_sel:[0,1,0] op_sel_hi:[1,1,1]
	v_pk_fma_f32 v[74:75], v[174:175], v[40:41], v[74:75] op_sel:[0,0,0] op_sel_hi:[1,0,1]
	v_pk_fma_f32 v[74:75], v[176:177], v[40:41], v[74:75] op_sel:[0,1,0] op_sel_hi:[1,1,1]
	v_pk_fma_f32 v[74:75], v[178:179], v[42:43], v[74:75] op_sel:[0,0,0] op_sel_hi:[1,0,1]
	v_pk_fma_f32 v[74:75], v[180:181], v[42:43], v[74:75] op_sel:[0,1,0] op_sel_hi:[1,1,1]
	v_fmac_f32_e32 v73, v182, v72
	v_pk_fma_f32 v[74:75], v[184:185], v[72:73], v[74:75] op_sel:[0,0,0] op_sel_hi:[1,0,1]
	v_pk_fma_f32 v[74:75], v[186:187], v[72:73], v[74:75] op_sel:[0,1,0] op_sel_hi:[1,1,1]
	v_fmac_f32_e32 v75, v183, v74
	v_cndmask_b32_e64 v56, v72, v138, s[98:99]
	v_cndmask_b32_e64 v57, v73, v139, s[98:99]
	v_cndmask_b32_e64 v58, v74, v140, s[98:99]
	v_cndmask_b32_e64 v59, v75, v141, s[98:99]
	v_mov_b32_e32 v252, v72
	v_mov_b32_e32 v253, v73
	v_mov_b32_e32 v254, v74
	v_mov_b32_e32 v255, v75
	v_mfma_f32_16x16x4_f32 v[208:211], v190, v56, v[208:211]
	v_mfma_f32_16x16x4_f32 v[212:215], v194, v56, v[212:215]
	v_mfma_f32_16x16x4_f32 v[216:219], v198, v56, v[216:219]
	v_mfma_f32_16x16x4_f32 v[220:223], v202, v56, v[220:223]
	v_permlane32_swap_b32_e32 v252, v254
	v_permlane32_swap_b32_e32 v253, v255
	v_mfma_f32_16x16x4_f32 v[208:211], v191, v57, v[208:211]
	v_mfma_f32_16x16x4_f32 v[212:215], v195, v57, v[212:215]
	v_mfma_f32_16x16x4_f32 v[216:219], v199, v57, v[216:219]
	v_mfma_f32_16x16x4_f32 v[220:223], v203, v57, v[220:223]
	v_mfma_f32_16x16x4_f32 v[208:211], v192, v58, v[208:211]
	v_mfma_f32_16x16x4_f32 v[212:215], v196, v58, v[212:215]
	v_mfma_f32_16x16x4_f32 v[216:219], v200, v58, v[216:219]
	v_mfma_f32_16x16x4_f32 v[220:223], v204, v58, v[220:223]
	v_mfma_f32_16x16x4_f32 v[208:211], v193, v59, v[208:211]
	v_mfma_f32_16x16x4_f32 v[212:215], v197, v59, v[212:215]
	v_mfma_f32_16x16x4_f32 v[216:219], v201, v59, v[216:219]
	v_mfma_f32_16x16x4_f32 v[220:223], v205, v59, v[220:223]
	v_mfma_f32_16x16x4_f32 v[248:251], v136, v252, v[72:75]
	v_mfma_f32_16x16x4_f32 v[248:251], v137, v253, v[248:251]
	s_waitcnt lgkmcnt(0)
	s_nop 4
	v_pk_mul_f32 v[208:209], v[208:209], v[144:145]
	v_pk_mul_f32 v[210:211], v[210:211], v[146:147]
	s_nop 0
	v_mfma_f32_16x16x4_f32 v[240:243], v90, v208, v[240:243]
	v_pk_mul_f32 v[212:213], v[212:213], v[148:149]
	v_mfma_f32_16x16x4_f32 v[244:247], v91, v209, 0
	v_pk_mul_f32 v[214:215], v[214:215], v[150:151]
	v_mfma_f32_16x16x4_f32 v[240:243], v92, v210, v[240:243]
	v_pk_mul_f32 v[216:217], v[216:217], v[152:153]
	v_mfma_f32_16x16x4_f32 v[244:247], v93, v211, v[244:247]
	v_pk_mul_f32 v[218:219], v[218:219], v[154:155]
	v_mfma_f32_16x16x4_f32 v[240:243], v94, v212, v[240:243]
	v_pk_mul_f32 v[220:221], v[220:221], v[156:157]
	v_mfma_f32_16x16x4_f32 v[244:247], v95, v213, v[244:247]
	v_pk_mul_f32 v[222:223], v[222:223], v[158:159]
	v_mfma_f32_16x16x4_f32 v[240:243], v96, v214, v[240:243]
	s_mov_b64 exec, s[98:99]
	ds_write_b32 v231, v248 offset:2048
	ds_write_b32 v231, v249 offset:2304
	ds_write_b32 v231, v250 offset:2560
	ds_write_b32 v231, v251 offset:2816
	s_mov_b64 exec, -1
	ds_read_b128 v[190:193], v27 offset:4096
	ds_read_b128 v[194:197], v27 offset:5120
	v_mfma_f32_16x16x4_f32 v[244:247], v97, v215, v[244:247]
	ds_read_b128 v[198:201], v27 offset:6144
	ds_read_b128 v[202:205], v27 offset:7168
	v_mfma_f32_16x16x4_f32 v[240:243], v98, v216, v[240:243]
	ds_read_b64 v[134:135], v32 offset:9984
	ds_read_b64 v[136:137], v33 offset:9984
	ds_read_b32 v138, v230 offset:6144
	ds_read_b32 v139, v230 offset:6400
	v_mfma_f32_16x16x4_f32 v[244:247], v99, v217, v[244:247]
	ds_read_b32 v140, v230 offset:6656
	ds_read_b32 v141, v230 offset:6912
	ds_read_b32 v46, v239 offset:6144
	ds_read_b32 v47, v239 offset:6400
	v_mfma_f32_16x16x4_f32 v[240:243], v100, v218, v[240:243]
	ds_read_b128 v[144:147], v26 offset:9984
	ds_read_b128 v[148:151], v26 offset:11008
	ds_read_b128 v[152:155], v26 offset:12032
	ds_read_b128 v[156:159], v26 offset:13056
	v_mfma_f32_16x16x4_f32 v[244:247], v101, v219, v[244:247]
	ds_read_b32 v160, v29 offset:9988
	ds_read_b32 v161, v29 offset:10060
	ds_read_b64 v[162:163], v29 offset:9992
	ds_read_b64 v[164:165], v29 offset:10024
	v_mfma_f32_16x16x4_f32 v[240:243], v102, v220, v[240:243]
	ds_read_b32 v182, v31 offset:9988
	ds_read_b32 v183, v31 offset:10060
	ds_read_b64 v[184:185], v31 offset:9992
	ds_read_b64 v[186:187], v31 offset:10024
	v_mfma_f32_16x16x4_f32 v[244:247], v103, v221, v[244:247]
	ds_read_b64 v[166:167], v30 offset:9984
	ds_read_b64 v[168:169], v30 offset:10016
	ds_read_b64 v[170:171], v30 offset:10048
	ds_read_b64 v[172:173], v30 offset:10080
	v_mfma_f32_16x16x4_f32 v[240:243], v104, v222, v[240:243]
	ds_read_b64 v[174:175], v30 offset:9992
	ds_read_b64 v[176:177], v30 offset:10024
	ds_read_b64 v[178:179], v30 offset:10056
	ds_read_b64 v[180:181], v30 offset:10088
	v_mfma_f32_16x16x4_f32 v[244:247], v105, v223, v[244:247]
	s_nop 9
	v_pk_add_f32 v[240:241], v[240:241], v[244:245]
	v_pk_add_f32 v[242:243], v[242:243], v[246:247]
	v_fmac_f32_e32 v241, v106, v240
	v_pk_fma_f32 v[242:243], v[108:109], v[240:241], v[242:243] op_sel:[0,0,0] op_sel_hi:[1,0,1]
	v_pk_fma_f32 v[242:243], v[110:111], v[240:241], v[242:243] op_sel:[0,1,0] op_sel_hi:[1,1,1]
	v_fmac_f32_e32 v243, v107, v242
	ds_bpermute_b32 v40, v232, v240
	ds_bpermute_b32 v41, v232, v241
	ds_bpermute_b32 v42, v232, v242
	ds_bpermute_b32 v43, v232, v243
	ds_read_b128 v[90:93], v28
	ds_read_b128 v[94:97], v28 offset:64
	ds_read_b128 v[98:101], v28 offset:128
	ds_read_b128 v[102:105], v28 offset:192
	s_waitcnt lgkmcnt(14)
	v_mfma_f32_16x16x4_f32 v[72:75], v134, v46, 0
	v_mfma_f32_16x16x4_f32 v[72:75], v135, v47, v[72:75]
	s_waitcnt lgkmcnt(6)
	v_pk_fma_f32 v[240:241], v[112:113], v[40:41], v[240:241] op_sel:[0,0,0] op_sel_hi:[1,0,1]
	v_pk_fma_f32 v[240:241], v[114:115], v[40:41], v[240:241] op_sel:[0,1,0] op_sel_hi:[1,1,1]
	s_waitcnt lgkmcnt(4)
	v_pk_fma_f32 v[240:241], v[116:117], v[42:43], v[240:241] op_sel:[0,0,0] op_sel_hi:[1,0,1]
	v_pk_fma_f32 v[240:241], v[118:119], v[42:43], v[240:241] op_sel:[0,1,0] op_sel_hi:[1,1,1]
	v_pk_fma_f32 v[242:243], v[120:121], v[40:41], v[242:243] op_sel:[0,0,0] op_sel_hi:[1,0,1]
	v_pk_fma_f32 v[242:243], v[122:123], v[40:41], v[242:243] op_sel:[0,1,0] op_sel_hi:[1,1,1]
	v_pk_fma_f32 v[242:243], v[124:125], v[42:43], v[242:243] op_sel:[0,0,0] op_sel_hi:[1,0,1]
	v_pk_fma_f32 v[242:243], v[126:127], v[42:43], v[242:243] op_sel:[0,1,0] op_sel_hi:[1,1,1]
	v_fmac_f32_e32 v241, v128, v240
	v_pk_fma_f32 v[242:243], v[130:131], v[240:241], v[242:243] op_sel:[0,0,0] op_sel_hi:[1,0,1]
	v_pk_fma_f32 v[242:243], v[132:133], v[240:241], v[242:243] op_sel:[0,1,0] op_sel_hi:[1,1,1]
	v_fmac_f32_e32 v243, v129, v242
	v_cndmask_b32_e64 v56, v240, v84, s[98:99]
	v_cndmask_b32_e64 v57, v241, v85, s[98:99]
	v_cndmask_b32_e64 v58, v242, v86, s[98:99]
	v_cndmask_b32_e64 v59, v243, v87, s[98:99]
	v_mov_b32_e32 v252, v240
	v_mov_b32_e32 v253, v241
	v_mov_b32_e32 v254, v242
	v_mov_b32_e32 v255, v243
	v_mfma_f32_16x16x4_f32 v[208:211], v190, v56, v[208:211]
	v_mfma_f32_16x16x4_f32 v[212:215], v194, v56, v[212:215]
	v_mfma_f32_16x16x4_f32 v[216:219], v198, v56, v[216:219]
	v_mfma_f32_16x16x4_f32 v[220:223], v202, v56, v[220:223]
	v_permlane32_swap_b32_e32 v252, v254
	v_permlane32_swap_b32_e32 v253, v255
	v_mfma_f32_16x16x4_f32 v[208:211], v191, v57, v[208:211]
	v_mfma_f32_16x16x4_f32 v[212:215], v195, v57, v[212:215]
	v_mfma_f32_16x16x4_f32 v[216:219], v199, v57, v[216:219]
	v_mfma_f32_16x16x4_f32 v[220:223], v203, v57, v[220:223]
	v_mfma_f32_16x16x4_f32 v[208:211], v192, v58, v[208:211]
	v_mfma_f32_16x16x4_f32 v[212:215], v196, v58, v[212:215]
	v_mfma_f32_16x16x4_f32 v[216:219], v200, v58, v[216:219]
	v_mfma_f32_16x16x4_f32 v[220:223], v204, v58, v[220:223]
	v_mfma_f32_16x16x4_f32 v[208:211], v193, v59, v[208:211]
	v_mfma_f32_16x16x4_f32 v[212:215], v197, v59, v[212:215]
	v_mfma_f32_16x16x4_f32 v[216:219], v201, v59, v[216:219]
	v_mfma_f32_16x16x4_f32 v[220:223], v205, v59, v[220:223]
	v_mfma_f32_16x16x4_f32 v[248:251], v82, v252, v[240:243]
	v_mfma_f32_16x16x4_f32 v[248:251], v83, v253, v[248:251]
	s_waitcnt lgkmcnt(0)
	s_nop 4
	v_pk_mul_f32 v[208:209], v[208:209], v[90:91]
	v_pk_mul_f32 v[210:211], v[210:211], v[92:93]
	s_nop 0
	v_mfma_f32_16x16x4_f32 v[72:75], v144, v208, v[72:75]
	v_pk_mul_f32 v[212:213], v[212:213], v[94:95]
	v_mfma_f32_16x16x4_f32 v[244:247], v145, v209, 0
	v_pk_mul_f32 v[214:215], v[214:215], v[96:97]
	v_mfma_f32_16x16x4_f32 v[72:75], v146, v210, v[72:75]
	v_pk_mul_f32 v[216:217], v[216:217], v[98:99]
	v_mfma_f32_16x16x4_f32 v[244:247], v147, v211, v[244:247]
	v_pk_mul_f32 v[218:219], v[218:219], v[100:101]
	v_mfma_f32_16x16x4_f32 v[72:75], v148, v212, v[72:75]
	v_pk_mul_f32 v[220:221], v[220:221], v[102:103]
	v_mfma_f32_16x16x4_f32 v[244:247], v149, v213, v[244:247]
	v_pk_mul_f32 v[222:223], v[222:223], v[104:105]
	v_mfma_f32_16x16x4_f32 v[72:75], v150, v214, v[72:75]
	s_mov_b64 exec, s[98:99]
	ds_write_b32 v231, v248 offset:4096
	ds_write_b32 v231, v249 offset:4352
	ds_write_b32 v231, v250 offset:4608
	ds_write_b32 v231, v251 offset:4864
	s_mov_b64 exec, -1
	ds_read_b128 v[190:193], v27 offset:14080
	ds_read_b128 v[194:197], v27 offset:15104
	v_mfma_f32_16x16x4_f32 v[244:247], v151, v215, v[244:247]
	ds_read_b128 v[198:201], v27 offset:16128
	ds_read_b128 v[202:205], v27 offset:17152
	v_mfma_f32_16x16x4_f32 v[72:75], v152, v216, v[72:75]
	v_mfma_f32_16x16x4_f32 v[244:247], v153, v217, v[244:247]
	v_mfma_f32_16x16x4_f32 v[72:75], v154, v218, v[72:75]
	v_mfma_f32_16x16x4_f32 v[244:247], v155, v219, v[244:247]
	v_mfma_f32_16x16x4_f32 v[72:75], v156, v220, v[72:75]
	v_mfma_f32_16x16x4_f32 v[244:247], v157, v221, v[244:247]
	v_mfma_f32_16x16x4_f32 v[72:75], v158, v222, v[72:75]
	v_mfma_f32_16x16x4_f32 v[244:247], v159, v223, v[244:247]
	s_nop 9
	v_pk_add_f32 v[72:73], v[72:73], v[244:245]
	v_pk_add_f32 v[74:75], v[74:75], v[246:247]
	v_fmac_f32_e32 v73, v160, v72
	v_pk_fma_f32 v[74:75], v[162:163], v[72:73], v[74:75] op_sel:[0,0,0] op_sel_hi:[1,0,1]
	v_pk_fma_f32 v[74:75], v[164:165], v[72:73], v[74:75] op_sel:[0,1,0] op_sel_hi:[1,1,1]
	v_fmac_f32_e32 v75, v161, v74
	ds_bpermute_b32 v40, v232, v72
	ds_bpermute_b32 v41, v232, v73
	ds_bpermute_b32 v42, v232, v74
	ds_bpermute_b32 v43, v232, v75
	ds_read_b128 v[144:147], v28 offset:9984
	ds_read_b128 v[148:151], v28 offset:10048
	ds_read_b128 v[152:155], v28 offset:10112
	ds_read_b128 v[156:159], v28 offset:10176
	s_waitcnt lgkmcnt(6)
	v_pk_fma_f32 v[72:73], v[166:167], v[40:41], v[72:73] op_sel:[0,0,0] op_sel_hi:[1,0,1]
	v_pk_fma_f32 v[72:73], v[168:169], v[40:41], v[72:73] op_sel:[0,1,0] op_sel_hi:[1,1,1]
	s_waitcnt lgkmcnt(4)
	v_pk_fma_f32 v[72:73], v[170:171], v[42:43], v[72:73] op_sel:[0,0,0] op_sel_hi:[1,0,1]
	v_pk_fma_f32 v[72:73], v[172:173], v[42:43], v[72:73] op_sel:[0,1,0] op_sel_hi:[1,1,1]
	v_pk_fma_f32 v[74:75], v[174:175], v[40:41], v[74:75] op_sel:[0,0,0] op_sel_hi:[1,0,1]
	v_pk_fma_f32 v[74:75], v[176:177], v[40:41], v[74:75] op_sel:[0,1,0] op_sel_hi:[1,1,1]
	v_pk_fma_f32 v[74:75], v[178:179], v[42:43], v[74:75] op_sel:[0,0,0] op_sel_hi:[1,0,1]
	v_pk_fma_f32 v[74:75], v[180:181], v[42:43], v[74:75] op_sel:[0,1,0] op_sel_hi:[1,1,1]
	v_fmac_f32_e32 v73, v182, v72
	v_pk_fma_f32 v[74:75], v[184:185], v[72:73], v[74:75] op_sel:[0,0,0] op_sel_hi:[1,0,1]
	v_pk_fma_f32 v[74:75], v[186:187], v[72:73], v[74:75] op_sel:[0,1,0] op_sel_hi:[1,1,1]
	v_fmac_f32_e32 v75, v183, v74
	v_cndmask_b32_e64 v56, v72, v138, s[98:99]
	v_cndmask_b32_e64 v57, v73, v139, s[98:99]
	v_cndmask_b32_e64 v58, v74, v140, s[98:99]
	v_cndmask_b32_e64 v59, v75, v141, s[98:99]
	v_mov_b32_e32 v252, v72
	v_mov_b32_e32 v253, v73
	v_mov_b32_e32 v254, v74
	v_mov_b32_e32 v255, v75
	v_mfma_f32_16x16x4_f32 v[208:211], v190, v56, v[208:211]
	v_mfma_f32_16x16x4_f32 v[212:215], v194, v56, v[212:215]
	v_mfma_f32_16x16x4_f32 v[216:219], v198, v56, v[216:219]
	v_mfma_f32_16x16x4_f32 v[220:223], v202, v56, v[220:223]
	v_permlane32_swap_b32_e32 v252, v254
	v_permlane32_swap_b32_e32 v253, v255
	v_mfma_f32_16x16x4_f32 v[208:211], v191, v57, v[208:211]
	v_mfma_f32_16x16x4_f32 v[212:215], v195, v57, v[212:215]
	v_mfma_f32_16x16x4_f32 v[216:219], v199, v57, v[216:219]
	v_mfma_f32_16x16x4_f32 v[220:223], v203, v57, v[220:223]
	v_mfma_f32_16x16x4_f32 v[208:211], v192, v58, v[208:211]
	v_mfma_f32_16x16x4_f32 v[212:215], v196, v58, v[212:215]
	v_mfma_f32_16x16x4_f32 v[216:219], v200, v58, v[216:219]
	v_mfma_f32_16x16x4_f32 v[220:223], v204, v58, v[220:223]
	v_mfma_f32_16x16x4_f32 v[208:211], v193, v59, v[208:211]
	v_mfma_f32_16x16x4_f32 v[212:215], v197, v59, v[212:215]
	v_mfma_f32_16x16x4_f32 v[216:219], v201, v59, v[216:219]
	v_mfma_f32_16x16x4_f32 v[220:223], v205, v59, v[220:223]
	v_mfma_f32_16x16x4_f32 v[248:251], v136, v252, v[72:75]
	v_mfma_f32_16x16x4_f32 v[248:251], v137, v253, v[248:251]
	s_waitcnt lgkmcnt(0)
	s_nop 4
	v_pk_mul_f32 v[208:209], v[208:209], v[144:145]
	v_pk_mul_f32 v[210:211], v[210:211], v[146:147]
	v_pk_mul_f32 v[212:213], v[212:213], v[148:149]
	v_pk_mul_f32 v[214:215], v[214:215], v[150:151]
	v_pk_mul_f32 v[216:217], v[216:217], v[152:153]
	v_pk_mul_f32 v[218:219], v[218:219], v[154:155]
	v_pk_mul_f32 v[220:221], v[220:221], v[156:157]
	v_pk_mul_f32 v[222:223], v[222:223], v[158:159]
	s_mov_b64 exec, s[98:99]
	ds_write_b32 v231, v248 offset:6144
	ds_write_b32 v231, v249 offset:6400
	ds_write_b32 v231, v250 offset:6656
	ds_write_b32 v231, v251 offset:6912
	s_mov_b64 exec, -1
	s_branch .LBB0_655
